# epilogue stores of the output GEMM and of the XR/GR input-projection tiles use SGPR base + 32-bit VGPR offset instead of 64-bit VGPR addresses (one address dword less per store)
# speedup vs baseline: 1.0023x; 1.0007x over previous
; __device__ __forceinline__ unsigned cvt_pk_bf16(float lo, float hi) { unsigned r; asm volatile("v_cvt_pk_bf16_f32 %0, %1, %2" : "=v"(r) : "v"(lo), "v"(hi)); return r; }
;     __device__ __forceinline__ void operator()(const pg8::f32x4 (&acc)[2][2][4][2], const pg8::Unit& u, int wr, int wc, int fr_, int fq_) const {
;     ...
; #pragma unroll
;             for (int ai = 0; ai < 2; ++ai)
; #pragma unroll
;                 for (int m = 0; m < 4; ++m) { bf16_t* rowp = dst + (size_t)(row0 + ai * HALF + m * 16) * pitch + col0;
; #pragma unroll
;                     for (int bj = 0; bj < 2; ++bj) { const f32x4 v0 = acc[ai][bj][m][0] * ascale + bv[bj][0], v1 = acc[ai][bj][m][1] * ascale + bv[bj][1];
;                         u32x4 w; w.x = cvt_pk_bf16(v0[0], v0[1]); w.y = cvt_pk_bf16(v0[2], v0[3]); w.z = cvt_pk_bf16(v1[0], v1[1]); w.w = cvt_pk_bf16(v1[2], v1[3]);
;                         __builtin_nontemporal_store(w, (u32x4*)(rowp + bj * HALF)); } }
.LBB0_389:
	v_add_u32_e32 v144, s65, v144
	v_ashrrev_i32_e32 v147, 31, v172
	v_ashrrev_i32_e32 v145, 31, v144
	v_mul_lo_u32 v147, s66, v147
	v_mad_u64_u32 v[148:149], s[6:7], s66, v172, 0
	v_lshl_add_u64 v[144:145], v[144:145], 1, s[68:69]
	v_add3_u32 v149, v149, v147, v163
	v_lshl_add_u64 v[152:153], v[148:149], 1, v[144:145]
	s_waitcnt vmcnt(2)
	v_pk_add_f32 v[148:149], v[132:133], v[92:93]
	v_pk_add_f32 v[150:151], v[134:135], v[94:95]
	v_cvt_pk_bf16_f32 v148, v148, v149
	v_pk_add_f32 v[154:155], v[130:131], v[86:87]
	v_cvt_pk_bf16_f32 v149, v150, v151
	v_pk_add_f32 v[156:157], v[128:129], v[84:85]
	v_add_u32_e32 v147, 16, v172
	v_cvt_pk_bf16_f32 v150, v156, v157
	v_cvt_pk_bf16_f32 v151, v154, v155
	v_subrev_u32_e32 v207, s68, v152
	global_store_dwordx4 v207, v[148:151], s[68:69] nt
	s_waitcnt vmcnt(2)
	v_pk_add_f32 v[154:155], v[138:139], v[82:83]
	v_pk_add_f32 v[156:157], v[136:137], v[80:81]
	s_waitcnt vmcnt(1)
	v_pk_add_f32 v[148:149], v[140:141], v[88:89]
	v_pk_add_f32 v[150:151], v[142:143], v[90:91]
	v_cvt_pk_bf16_f32 v148, v148, v149
	s_mov_b64 s[70:71], 0
	v_cvt_pk_bf16_f32 v149, v150, v151
	v_cvt_pk_bf16_f32 v150, v156, v157
	v_cvt_pk_bf16_f32 v151, v154, v155
	global_store_dwordx4 v207, v[148:151], s[68:69] offset:256 nt
	v_pk_add_f32 v[154:155], v[114:115], v[86:87]
	v_pk_add_f32 v[156:157], v[112:113], v[84:85]
	v_ashrrev_i32_e32 v148, 31, v147
	v_mul_lo_u32 v150, s66, v148
	v_mul_lo_u32 v151, s67, v147
	v_mad_u64_u32 v[148:149], s[6:7], s66, v147, 0
	v_add3_u32 v149, v149, v150, v151
	v_lshl_add_u64 v[152:153], v[148:149], 1, v[144:145]
	v_pk_add_f32 v[148:149], v[116:117], v[92:93]
	v_pk_add_f32 v[150:151], v[118:119], v[94:95]
	v_cvt_pk_bf16_f32 v148, v148, v149
	v_add_u32_e32 v147, 32, v172
	v_cvt_pk_bf16_f32 v149, v150, v151
	v_cvt_pk_bf16_f32 v150, v156, v157
	v_cvt_pk_bf16_f32 v151, v154, v155
	v_subrev_u32_e32 v206, s68, v152
	global_store_dwordx4 v206, v[148:151], s[68:69] nt
	v_pk_add_f32 v[154:155], v[122:123], v[82:83]
	v_pk_add_f32 v[156:157], v[120:121], v[80:81]
	v_pk_add_f32 v[148:149], v[124:125], v[88:89]
	v_pk_add_f32 v[150:151], v[126:127], v[90:91]
	v_cvt_pk_bf16_f32 v148, v148, v149
	s_nop 0
	v_cvt_pk_bf16_f32 v149, v150, v151
	v_cvt_pk_bf16_f32 v150, v156, v157
	v_cvt_pk_bf16_f32 v151, v154, v155
	global_store_dwordx4 v206, v[148:151], s[68:69] offset:256 nt
	v_pk_add_f32 v[154:155], v[98:99], v[86:87]
	v_pk_add_f32 v[156:157], v[96:97], v[84:85]
	v_ashrrev_i32_e32 v148, 31, v147
	v_mul_lo_u32 v150, s66, v148
	v_mul_lo_u32 v151, s67, v147
	v_mad_u64_u32 v[148:149], s[6:7], s66, v147, 0
	v_add3_u32 v149, v149, v150, v151
	v_lshl_add_u64 v[152:153], v[148:149], 1, v[144:145]
	v_pk_add_f32 v[148:149], v[100:101], v[92:93]
	v_pk_add_f32 v[150:151], v[102:103], v[94:95]
	v_cvt_pk_bf16_f32 v148, v148, v149
	v_add_u32_e32 v147, 48, v172
	v_cvt_pk_bf16_f32 v149, v150, v151
	v_cvt_pk_bf16_f32 v150, v156, v157
	v_cvt_pk_bf16_f32 v151, v154, v155
	v_subrev_u32_e32 v207, s68, v152
	global_store_dwordx4 v207, v[148:151], s[68:69] nt
	v_pk_add_f32 v[154:155], v[106:107], v[82:83]
	v_pk_add_f32 v[156:157], v[104:105], v[80:81]
	v_pk_add_f32 v[148:149], v[108:109], v[88:89]
	v_pk_add_f32 v[150:151], v[110:111], v[90:91]
	v_cvt_pk_bf16_f32 v148, v148, v149
	s_nop 0
	v_cvt_pk_bf16_f32 v149, v150, v151
	v_cvt_pk_bf16_f32 v150, v156, v157
	v_cvt_pk_bf16_f32 v151, v154, v155
	global_store_dwordx4 v207, v[148:151], s[68:69] offset:256 nt
	v_pk_add_f32 v[154:155], v[66:67], v[86:87]
	v_pk_add_f32 v[156:157], v[64:65], v[84:85]
	v_ashrrev_i32_e32 v148, 31, v147
	v_mul_lo_u32 v150, s66, v148
	v_mul_lo_u32 v151, s67, v147
	v_mad_u64_u32 v[148:149], s[6:7], s66, v147, 0
	v_add3_u32 v149, v149, v150, v151
	v_lshl_add_u64 v[152:153], v[148:149], 1, v[144:145]
	v_pk_add_f32 v[148:149], v[68:69], v[92:93]
	v_pk_add_f32 v[150:151], v[70:71], v[94:95]
	v_cvt_pk_bf16_f32 v148, v148, v149
	v_add_u32_e32 v147, 0x80, v172
	v_cvt_pk_bf16_f32 v149, v150, v151
	v_cvt_pk_bf16_f32 v150, v156, v157
	v_cvt_pk_bf16_f32 v151, v154, v155
	v_subrev_u32_e32 v206, s68, v152
	global_store_dwordx4 v206, v[148:151], s[68:69] nt
	v_pk_add_f32 v[154:155], v[74:75], v[82:83]
	v_pk_add_f32 v[156:157], v[72:73], v[80:81]
	v_pk_add_f32 v[148:149], v[76:77], v[88:89]
	v_pk_add_f32 v[150:151], v[78:79], v[90:91]
	v_cvt_pk_bf16_f32 v148, v148, v149
	s_nop 0
	v_cvt_pk_bf16_f32 v149, v150, v151
; __device__ __forceinline__ unsigned cvt_pk_bf16(float lo, float hi) { unsigned r; asm volatile("v_cvt_pk_bf16_f32 %0, %1, %2" : "=v"(r) : "v"(lo), "v"(hi)); return r; }
;     __device__ __forceinline__ void operator()(const pg8::f32x4 (&acc)[2][2][4][2], const pg8::Unit& u, int wr, int wc, int fr_, int fq_) const {
;     ...
; #pragma unroll
;             for (int ai = 0; ai < 2; ++ai)
; #pragma unroll
;                 for (int m = 0; m < 4; ++m) { bf16_t* rowp = dst + (size_t)(row0 + ai * HALF + m * 16) * pitch + col0;
; #pragma unroll
;                     for (int bj = 0; bj < 2; ++bj) { const f32x4 v0 = acc[ai][bj][m][0] * ascale + bv[bj][0], v1 = acc[ai][bj][m][1] * ascale + bv[bj][1];
;                         u32x4 w; w.x = cvt_pk_bf16(v0[0], v0[1]); w.y = cvt_pk_bf16(v0[2], v0[3]); w.z = cvt_pk_bf16(v1[0], v1[1]); w.w = cvt_pk_bf16(v1[2], v1[3]);
;                         __builtin_nontemporal_store(w, (u32x4*)(rowp + bj * HALF)); } }
	v_cvt_pk_bf16_f32 v150, v156, v157
	v_cvt_pk_bf16_f32 v151, v154, v155
	global_store_dwordx4 v206, v[148:151], s[68:69] offset:256 nt
	v_pk_add_f32 v[154:155], v[50:51], v[86:87]
	v_pk_add_f32 v[156:157], v[48:49], v[84:85]
	v_ashrrev_i32_e32 v148, 31, v147
	v_mul_lo_u32 v150, s66, v148
	v_mul_lo_u32 v151, s67, v147
	v_mad_u64_u32 v[148:149], s[6:7], s66, v147, 0
	v_add3_u32 v149, v149, v150, v151
	v_lshl_add_u64 v[152:153], v[148:149], 1, v[144:145]
	v_pk_add_f32 v[148:149], v[52:53], v[92:93]
	v_pk_add_f32 v[150:151], v[54:55], v[94:95]
	v_cvt_pk_bf16_f32 v148, v148, v149
	v_add_u32_e32 v147, 0x90, v172
	v_cvt_pk_bf16_f32 v149, v150, v151
	v_cvt_pk_bf16_f32 v150, v156, v157
	v_cvt_pk_bf16_f32 v151, v154, v155
	v_subrev_u32_e32 v207, s68, v152
	global_store_dwordx4 v207, v[148:151], s[68:69] nt
	v_pk_add_f32 v[154:155], v[58:59], v[82:83]
	v_pk_add_f32 v[156:157], v[56:57], v[80:81]
	v_pk_add_f32 v[148:149], v[60:61], v[88:89]
	v_pk_add_f32 v[150:151], v[62:63], v[90:91]
	v_cvt_pk_bf16_f32 v148, v148, v149
	s_nop 0
	v_cvt_pk_bf16_f32 v149, v150, v151
	v_cvt_pk_bf16_f32 v150, v156, v157
	v_cvt_pk_bf16_f32 v151, v154, v155
	global_store_dwordx4 v207, v[148:151], s[68:69] offset:256 nt
	v_pk_add_f32 v[154:155], v[34:35], v[86:87]
	v_pk_add_f32 v[156:157], v[32:33], v[84:85]
	v_ashrrev_i32_e32 v148, 31, v147
	v_mul_lo_u32 v150, s66, v148
	v_mul_lo_u32 v151, s67, v147
	v_mad_u64_u32 v[148:149], s[6:7], s66, v147, 0
	v_add3_u32 v149, v149, v150, v151
	v_lshl_add_u64 v[152:153], v[148:149], 1, v[144:145]
	v_pk_add_f32 v[148:149], v[36:37], v[92:93]
	v_pk_add_f32 v[150:151], v[38:39], v[94:95]
	v_cvt_pk_bf16_f32 v148, v148, v149
	v_add_u32_e32 v147, 0xa0, v172
	v_cvt_pk_bf16_f32 v149, v150, v151
	v_cvt_pk_bf16_f32 v150, v156, v157
	v_cvt_pk_bf16_f32 v151, v154, v155
	v_subrev_u32_e32 v206, s68, v152
	global_store_dwordx4 v206, v[148:151], s[68:69] nt
	v_pk_add_f32 v[154:155], v[42:43], v[82:83]
	v_pk_add_f32 v[156:157], v[40:41], v[80:81]
	v_pk_add_f32 v[148:149], v[44:45], v[88:89]
	v_pk_add_f32 v[150:151], v[46:47], v[90:91]
	v_cvt_pk_bf16_f32 v148, v148, v149
	s_nop 0
	v_cvt_pk_bf16_f32 v149, v150, v151
	v_cvt_pk_bf16_f32 v150, v156, v157
	v_cvt_pk_bf16_f32 v151, v154, v155
	global_store_dwordx4 v206, v[148:151], s[68:69] offset:256 nt
	v_pk_add_f32 v[154:155], v[18:19], v[86:87]
	v_pk_add_f32 v[156:157], v[16:17], v[84:85]
	v_ashrrev_i32_e32 v148, 31, v147
	v_mul_lo_u32 v150, s66, v148
	v_mul_lo_u32 v151, s67, v147
	v_mad_u64_u32 v[148:149], s[6:7], s66, v147, 0
	v_add3_u32 v149, v149, v150, v151
	v_lshl_add_u64 v[152:153], v[148:149], 1, v[144:145]
	v_pk_add_f32 v[148:149], v[20:21], v[92:93]
	v_pk_add_f32 v[150:151], v[22:23], v[94:95]
	v_cvt_pk_bf16_f32 v148, v148, v149
	v_add_u32_e32 v147, 0xb0, v172
	v_cvt_pk_bf16_f32 v149, v150, v151
	v_cvt_pk_bf16_f32 v150, v156, v157
	v_cvt_pk_bf16_f32 v151, v154, v155
	v_subrev_u32_e32 v207, s68, v152
	global_store_dwordx4 v207, v[148:151], s[68:69] nt
	v_pk_add_f32 v[154:155], v[26:27], v[82:83]
	v_pk_add_f32 v[156:157], v[24:25], v[80:81]
	v_pk_add_f32 v[148:149], v[28:29], v[88:89]
	v_pk_add_f32 v[150:151], v[30:31], v[90:91]
	v_cvt_pk_bf16_f32 v148, v148, v149
	s_nop 0
	v_cvt_pk_bf16_f32 v149, v150, v151
	v_cvt_pk_bf16_f32 v150, v156, v157
	v_cvt_pk_bf16_f32 v151, v154, v155
	global_store_dwordx4 v207, v[148:151], s[68:69] offset:256 nt
	v_pk_add_f32 v[152:153], v[2:3], v[86:87]
	v_pk_add_f32 v[154:155], v[0:1], v[84:85]
	v_ashrrev_i32_e32 v148, 31, v147
	v_mul_lo_u32 v150, s66, v148
	v_mul_lo_u32 v151, s67, v147
	v_mad_u64_u32 v[148:149], s[6:7], s66, v147, 0
	v_add3_u32 v149, v149, v150, v151
	v_lshl_add_u64 v[144:145], v[148:149], 1, v[144:145]
	v_pk_add_f32 v[150:151], v[6:7], v[94:95]
	v_pk_add_f32 v[148:149], v[4:5], v[92:93]
	s_nop 0
	v_cvt_pk_bf16_f32 v148, v148, v149
	v_cvt_pk_bf16_f32 v149, v150, v151
	v_cvt_pk_bf16_f32 v150, v154, v155
	v_cvt_pk_bf16_f32 v151, v152, v153
	v_subrev_u32_e32 v206, s68, v144
	global_store_dwordx4 v206, v[148:151], s[68:69] nt
	v_pk_add_f32 v[152:153], v[10:11], v[82:83]
	v_pk_add_f32 v[154:155], v[8:9], v[80:81]
	v_pk_add_f32 v[150:151], v[14:15], v[90:91]
	v_pk_add_f32 v[148:149], v[12:13], v[88:89]
	s_nop 0
	v_cvt_pk_bf16_f32 v148, v148, v149
	v_cvt_pk_bf16_f32 v149, v150, v151
	v_cvt_pk_bf16_f32 v150, v154, v155
	v_cvt_pk_bf16_f32 v151, v152, v153
	global_store_dwordx4 v206, v[148:151], s[68:69] offset:256 nt

;     __device__ __forceinline__ void operator()(pg8::f32x4 (&acc)[2][2][4][2], const pg8::Unit& u, int wr, int wc, int fr_, int fq_) const {
;     ...
; #pragma unroll
;         for (int ai = 0; ai < 2; ++ai)
; #pragma unroll
;             for (int m = 0; m < 4; ++m) { const int r = ai * HALF + wr * 64 + m * 16 + fr; const f32x2v sr = S[r]; const float nm = -sr.x * sr.y; const size_t off = (size_t)(u.pm * BM + r) * DM + col0;
; #pragma unroll
;                 for (int bj = 0; bj < 2; ++bj)
; #pragma unroll
;                     for (int n = 0; n < 2; ++n) { const f32x4 o = (acc[ai][bj][m][n] * sr.y + nm) * gv[bj][n] + lb[bj][n];
;                         *(f32x4*)(out + off + bj * HALF + n * 16) = o; } }
.LBB0_977:
	s_or_b64 exec, exec, s[6:7]
	v_or_b32_e32 v176, s67, v187
	s_add_i32 s4, 0, 0x22240
	s_waitcnt lgkmcnt(0)
	s_barrier
	v_lshl_add_u32 v177, v176, 3, s4
	ds_read2st64_b64 v[160:163], v177 offset1:2
	v_add_u32_e32 v172, s52, v176
	v_ashrrev_i32_e32 v173, 31, v172
	v_lshlrev_b64 v[174:175], 12, v[172:173]
	s_nop 0
	s_waitcnt lgkmcnt(0)
	v_mul_f32_e64 v166, v161, -v160
	v_pk_fma_f32 v[152:153], v[152:153], v[160:161], v[166:167] op_sel:[0,1,0] op_sel_hi:[1,1,0]
	v_pk_fma_f32 v[154:155], v[154:155], v[160:161], v[166:167] op_sel:[0,1,0] op_sel_hi:[1,1,0]
	v_lshl_add_u64 v[174:175], v[174:175], 0, v[170:171]
	s_waitcnt vmcnt(4)
	v_pk_fma_f32 v[154:155], v[130:131], v[154:155], v[134:135]
	v_pk_fma_f32 v[152:153], v[128:129], v[152:153], v[132:133]
	v_pk_fma_f32 v[144:145], v[144:145], v[160:161], v[166:167] op_sel:[0,1,0] op_sel_hi:[1,1,0]
	v_pk_fma_f32 v[146:147], v[146:147], v[160:161], v[166:167] op_sel:[0,1,0] op_sel_hi:[1,1,0]
	global_store_dwordx4 v174, v[152:155], s[30:31] offset:64
	s_waitcnt vmcnt(1)
	v_pk_fma_f32 v[146:147], v[114:115], v[146:147], v[118:119]
	v_pk_fma_f32 v[144:145], v[112:113], v[144:145], v[116:117]
	v_or_b32_e32 v153, 16, v176
	global_store_dwordx4 v174, v[144:147], s[30:31] offset:576
	v_pk_fma_f32 v[156:157], v[156:157], v[160:161], v[166:167] op_sel:[0,1,0] op_sel_hi:[1,1,0]
	v_pk_fma_f32 v[158:159], v[158:159], v[160:161], v[166:167] op_sel:[0,1,0] op_sel_hi:[1,1,0]
	v_lshl_add_u32 v144, v153, 3, s4
	ds_read_b64 v[144:145], v144
	v_add_u32_e32 v154, s52, v153
	v_pk_fma_f32 v[158:159], v[138:139], v[158:159], v[142:143]
	v_pk_fma_f32 v[156:157], v[136:137], v[156:157], v[140:141]
	v_pk_fma_f32 v[148:149], v[148:149], v[160:161], v[166:167] op_sel:[0,1,0] op_sel_hi:[1,1,0]
	v_pk_fma_f32 v[150:151], v[150:151], v[160:161], v[166:167] op_sel:[0,1,0] op_sel_hi:[1,1,0]
	v_ashrrev_i32_e32 v155, 31, v154
	global_store_dwordx4 v174, v[156:159], s[30:31]
	v_pk_fma_f32 v[150:151], v[122:123], v[150:151], v[126:127]
	v_pk_fma_f32 v[148:149], v[120:121], v[148:149], v[124:125]
	v_or_b32_e32 v156, 32, v176
	v_or_b32_e32 v157, 48, v176
	s_waitcnt lgkmcnt(0)
	v_mul_f32_e64 v152, v145, -v144
	v_lshlrev_b64 v[154:155], 12, v[154:155]
	global_store_dwordx4 v174, v[148:151], s[30:31] offset:512
	v_lshl_add_u32 v146, v156, 3, s4
	v_lshl_add_u32 v147, v157, 3, s4
	s_nop 0
	v_pk_fma_f32 v[16:17], v[16:17], v[144:145], v[152:153] op_sel:[0,1,0] op_sel_hi:[1,1,0]
	v_pk_fma_f32 v[18:19], v[18:19], v[144:145], v[152:153] op_sel:[0,1,0] op_sel_hi:[1,1,0]
	ds_read_b64 v[148:149], v146
	ds_read_b64 v[146:147], v147
	ds_read_b64 v[150:151], v177 offset:1408
	v_lshl_add_u64 v[154:155], v[154:155], 0, v[170:171]
	v_pk_fma_f32 v[18:19], v[114:115], v[18:19], v[118:119]
	v_pk_fma_f32 v[16:17], v[112:113], v[16:17], v[116:117]
	global_store_dwordx4 v154, v[16:19], s[30:31] offset:576
	v_pk_fma_f32 v[28:29], v[28:29], v[144:145], v[152:153] op_sel:[0,1,0] op_sel_hi:[1,1,0]
	v_pk_fma_f32 v[30:31], v[30:31], v[144:145], v[152:153] op_sel:[0,1,0] op_sel_hi:[1,1,0]
	v_add_u32_e32 v18, s52, v156
	v_ashrrev_i32_e32 v19, 31, v18
	s_waitcnt lgkmcnt(2)
	v_mul_f32_e64 v16, v149, -v148
	v_lshlrev_b64 v[18:19], 12, v[18:19]
	v_pk_fma_f32 v[0:1], v[0:1], v[148:149], v[16:17] op_sel:[0,1,0] op_sel_hi:[1,1,0]
	v_pk_fma_f32 v[2:3], v[2:3], v[148:149], v[16:17] op_sel:[0,1,0] op_sel_hi:[1,1,0]
	s_nop 0
	v_pk_fma_f32 v[2:3], v[138:139], v[2:3], v[142:143]
	v_pk_fma_f32 v[0:1], v[136:137], v[0:1], v[140:141]
	v_lshl_add_u64 v[18:19], v[18:19], 0, v[170:171]
	global_store_dwordx4 v18, v[0:3], s[30:31]
	v_pk_fma_f32 v[30:31], v[138:139], v[30:31], v[142:143]
	v_pk_fma_f32 v[28:29], v[136:137], v[28:29], v[140:141]
	v_pk_fma_f32 v[0:1], v[4:5], v[148:149], v[16:17] op_sel:[0,1,0] op_sel_hi:[1,1,0]
	v_pk_fma_f32 v[2:3], v[6:7], v[148:149], v[16:17] op_sel:[0,1,0] op_sel_hi:[1,1,0]
	v_pk_fma_f32 v[0:1], v[128:129], v[0:1], v[132:133]
	v_pk_fma_f32 v[2:3], v[130:131], v[2:3], v[134:135]
	global_store_dwordx4 v18, v[0:3], s[30:31] offset:64
	s_waitcnt lgkmcnt(1)
	v_mul_f32_e64 v4, v147, -v146
	global_store_dwordx4 v154, v[28:31], s[30:31]
	v_pk_fma_f32 v[0:1], v[8:9], v[148:149], v[16:17] op_sel:[0,1,0] op_sel_hi:[1,1,0]
	v_pk_fma_f32 v[2:3], v[10:11], v[148:149], v[16:17] op_sel:[0,1,0] op_sel_hi:[1,1,0]
	v_pk_fma_f32 v[0:1], v[120:121], v[0:1], v[124:125]
	v_pk_fma_f32 v[2:3], v[122:123], v[2:3], v[126:127]
	global_store_dwordx4 v18, v[0:3], s[30:31] offset:512
	v_pk_fma_f32 v[24:25], v[24:25], v[144:145], v[152:153] op_sel:[0,1,0] op_sel_hi:[1,1,0]
	v_pk_fma_f32 v[26:27], v[26:27], v[144:145], v[152:153] op_sel:[0,1,0] op_sel_hi:[1,1,0]
	v_pk_fma_f32 v[0:1], v[12:13], v[148:149], v[16:17] op_sel:[0,1,0] op_sel_hi:[1,1,0]
	v_pk_fma_f32 v[2:3], v[14:15], v[148:149], v[16:17] op_sel:[0,1,0] op_sel_hi:[1,1,0]
	v_pk_fma_f32 v[0:1], v[112:113], v[0:1], v[116:117]
	v_pk_fma_f32 v[2:3], v[114:115], v[2:3], v[118:119]
	global_store_dwordx4 v18, v[0:3], s[30:31] offset:576
	v_pk_fma_f32 v[26:27], v[130:131], v[26:27], v[134:135]
	v_pk_fma_f32 v[24:25], v[128:129], v[24:25], v[132:133]
	v_add_u32_e32 v0, s52, v157
	v_ashrrev_i32_e32 v1, 31, v0
	v_lshlrev_b64 v[6:7], 12, v[0:1]
	v_pk_fma_f32 v[0:1], v[32:33], v[146:147], v[4:5] op_sel:[0,1,0] op_sel_hi:[1,1,0]
	v_pk_fma_f32 v[2:3], v[34:35], v[146:147], v[4:5] op_sel:[0,1,0] op_sel_hi:[1,1,0]
	s_nop 0
	v_pk_fma_f32 v[2:3], v[138:139], v[2:3], v[142:143]
	v_pk_fma_f32 v[0:1], v[136:137], v[0:1], v[140:141]
	v_lshl_add_u64 v[6:7], v[6:7], 0, v[170:171]
	global_store_dwordx4 v6, v[0:3], s[30:31]
	global_store_dwordx4 v154, v[24:27], s[30:31] offset:64
	v_pk_fma_f32 v[20:21], v[20:21], v[144:145], v[152:153] op_sel:[0,1,0] op_sel_hi:[1,1,0]
;     __device__ __forceinline__ void operator()(pg8::f32x4 (&acc)[2][2][4][2], const pg8::Unit& u, int wr, int wc, int fr_, int fq_) const {
;     ...
; #pragma unroll
;         for (int ai = 0; ai < 2; ++ai)
; #pragma unroll
;             for (int m = 0; m < 4; ++m) { const int r = ai * HALF + wr * 64 + m * 16 + fr; const f32x2v sr = S[r]; const float nm = -sr.x * sr.y; const size_t off = (size_t)(u.pm * BM + r) * DM + col0;
; #pragma unroll
;                 for (int bj = 0; bj < 2; ++bj)
; #pragma unroll
;                     for (int n = 0; n < 2; ++n) { const f32x4 o = (acc[ai][bj][m][n] * sr.y + nm) * gv[bj][n] + lb[bj][n];
;                         *(f32x4*)(out + off + bj * HALF + n * 16) = o; } }
	v_pk_fma_f32 v[0:1], v[36:37], v[146:147], v[4:5] op_sel:[0,1,0] op_sel_hi:[1,1,0]
	v_pk_fma_f32 v[2:3], v[38:39], v[146:147], v[4:5] op_sel:[0,1,0] op_sel_hi:[1,1,0]
	v_pk_fma_f32 v[0:1], v[128:129], v[0:1], v[132:133]
	v_pk_fma_f32 v[2:3], v[130:131], v[2:3], v[134:135]
	global_store_dwordx4 v6, v[0:3], s[30:31] offset:64
	v_pk_fma_f32 v[22:23], v[22:23], v[144:145], v[152:153] op_sel:[0,1,0] op_sel_hi:[1,1,0]
	v_pk_fma_f32 v[20:21], v[120:121], v[20:21], v[124:125]
	v_pk_fma_f32 v[0:1], v[40:41], v[146:147], v[4:5] op_sel:[0,1,0] op_sel_hi:[1,1,0]
	v_pk_fma_f32 v[2:3], v[42:43], v[146:147], v[4:5] op_sel:[0,1,0] op_sel_hi:[1,1,0]
	v_pk_fma_f32 v[0:1], v[120:121], v[0:1], v[124:125]
	v_pk_fma_f32 v[2:3], v[122:123], v[2:3], v[126:127]
	global_store_dwordx4 v6, v[0:3], s[30:31] offset:512
	v_pk_fma_f32 v[22:23], v[122:123], v[22:23], v[126:127]
	global_store_dwordx4 v154, v[20:23], s[30:31] offset:512
	v_pk_fma_f32 v[0:1], v[44:45], v[146:147], v[4:5] op_sel:[0,1,0] op_sel_hi:[1,1,0]
	v_pk_fma_f32 v[2:3], v[46:47], v[146:147], v[4:5] op_sel:[0,1,0] op_sel_hi:[1,1,0]
	v_pk_fma_f32 v[0:1], v[112:113], v[0:1], v[116:117]
	v_pk_fma_f32 v[2:3], v[114:115], v[2:3], v[118:119]
	global_store_dwordx4 v6, v[0:3], s[30:31] offset:576
	v_mul_f32_e64 v4, v163, -v162
	v_pk_fma_f32 v[10:11], v[48:49], v[162:163], v[4:5] op_sel:[0,1,0] op_sel_hi:[1,1,0]
	v_add_u32_e32 v0, 0x80, v172
	v_ashrrev_i32_e32 v1, 31, v0
	v_lshlrev_b64 v[6:7], 12, v[0:1]
	v_pk_fma_f32 v[0:1], v[60:61], v[162:163], v[4:5] op_sel:[0,1,0] op_sel_hi:[1,1,0]
	v_pk_fma_f32 v[2:3], v[62:63], v[162:163], v[4:5] op_sel:[0,1,0] op_sel_hi:[1,1,0]
	s_nop 0
	v_pk_fma_f32 v[2:3], v[138:139], v[2:3], v[142:143]
	v_pk_fma_f32 v[0:1], v[136:137], v[0:1], v[140:141]
	v_lshl_add_u64 v[8:9], v[6:7], 0, v[170:171]
	global_store_dwordx4 v8, v[0:3], s[30:31]
	s_or_b64 s[4:5], s[14:15], s[0:1]
	s_and_b64 s[6:7], exec, s[0:1]
	v_pk_fma_f32 v[0:1], v[56:57], v[162:163], v[4:5] op_sel:[0,1,0] op_sel_hi:[1,1,0]
	v_pk_fma_f32 v[2:3], v[58:59], v[162:163], v[4:5] op_sel:[0,1,0] op_sel_hi:[1,1,0]
	v_pk_fma_f32 v[0:1], v[128:129], v[0:1], v[132:133]
	v_pk_fma_f32 v[2:3], v[130:131], v[2:3], v[134:135]
	global_store_dwordx4 v8, v[0:3], s[30:31] offset:64
	s_cselect_b32 s66, s66, s91
	s_and_b64 vcc, exec, s[4:5]
	v_pk_fma_f32 v[0:1], v[52:53], v[162:163], v[4:5] op_sel:[0,1,0] op_sel_hi:[1,1,0]
	v_pk_fma_f32 v[2:3], v[54:55], v[162:163], v[4:5] op_sel:[0,1,0] op_sel_hi:[1,1,0]
	v_pk_fma_f32 v[0:1], v[120:121], v[0:1], v[124:125]
	v_pk_fma_f32 v[2:3], v[122:123], v[2:3], v[126:127]
	global_store_dwordx4 v8, v[0:3], s[30:31] offset:512
	ds_read2_b64 v[0:3], v177 offset0:144 offset1:160
	v_pk_fma_f32 v[4:5], v[50:51], v[162:163], v[4:5] op_sel:[0,1,0] op_sel_hi:[1,1,0]
	s_nop 0
	v_pk_fma_f32 v[6:7], v[114:115], v[4:5], v[118:119]
	v_pk_fma_f32 v[4:5], v[112:113], v[10:11], v[116:117]
	global_store_dwordx4 v8, v[4:7], s[30:31] offset:576
	s_waitcnt lgkmcnt(0)
;     __device__ __forceinline__ void operator()(pg8::f32x4 (&acc)[2][2][4][2], const pg8::Unit& u, int wr, int wc, int fr_, int fq_) const {
;     ...
; #pragma unroll
;         for (int ai = 0; ai < 2; ++ai)
; #pragma unroll
;             for (int m = 0; m < 4; ++m) { const int r = ai * HALF + wr * 64 + m * 16 + fr; const f32x2v sr = S[r]; const float nm = -sr.x * sr.y; const size_t off = (size_t)(u.pm * BM + r) * DM + col0;
; #pragma unroll
;                 for (int bj = 0; bj < 2; ++bj)
; #pragma unroll
;                     for (int n = 0; n < 2; ++n) { const f32x4 o = (acc[ai][bj][m][n] * sr.y + nm) * gv[bj][n] + lb[bj][n];
;                         *(f32x4*)(out + off + bj * HALF + n * 16) = o; } }
	v_mul_f32_e64 v8, v1, -v0
	v_add_u32_e32 v4, 0x90, v172
	v_ashrrev_i32_e32 v5, 31, v4
	v_lshlrev_b64 v[10:11], 12, v[4:5]
	v_pk_fma_f32 v[4:5], v[64:65], v[0:1], v[8:9] op_sel:[0,1,0] op_sel_hi:[1,1,0]
	v_pk_fma_f32 v[6:7], v[66:67], v[0:1], v[8:9] op_sel:[0,1,0] op_sel_hi:[1,1,0]
	s_nop 0
	v_pk_fma_f32 v[6:7], v[138:139], v[6:7], v[142:143]
	v_pk_fma_f32 v[4:5], v[136:137], v[4:5], v[140:141]
	v_lshl_add_u64 v[10:11], v[10:11], 0, v[170:171]
	global_store_dwordx4 v10, v[4:7], s[30:31]
	s_nop 1
	v_pk_fma_f32 v[4:5], v[68:69], v[0:1], v[8:9] op_sel:[0,1,0] op_sel_hi:[1,1,0]
	v_pk_fma_f32 v[6:7], v[70:71], v[0:1], v[8:9] op_sel:[0,1,0] op_sel_hi:[1,1,0]
	v_pk_fma_f32 v[4:5], v[128:129], v[4:5], v[132:133]
	v_pk_fma_f32 v[6:7], v[130:131], v[6:7], v[134:135]
	global_store_dwordx4 v10, v[4:7], s[30:31] offset:64
	s_nop 1
	v_pk_fma_f32 v[4:5], v[72:73], v[0:1], v[8:9] op_sel:[0,1,0] op_sel_hi:[1,1,0]
	v_pk_fma_f32 v[6:7], v[74:75], v[0:1], v[8:9] op_sel:[0,1,0] op_sel_hi:[1,1,0]
	v_pk_fma_f32 v[4:5], v[120:121], v[4:5], v[124:125]
	v_pk_fma_f32 v[6:7], v[122:123], v[6:7], v[126:127]
	global_store_dwordx4 v10, v[4:7], s[30:31] offset:512
	s_nop 1
	v_pk_fma_f32 v[4:5], v[76:77], v[0:1], v[8:9] op_sel:[0,1,0] op_sel_hi:[1,1,0]
	v_pk_fma_f32 v[0:1], v[78:79], v[0:1], v[8:9] op_sel:[0,1,0] op_sel_hi:[1,1,0]
	v_pk_fma_f32 v[4:5], v[112:113], v[4:5], v[116:117]
	v_pk_fma_f32 v[6:7], v[114:115], v[0:1], v[118:119]
	global_store_dwordx4 v10, v[4:7], s[30:31] offset:576
	v_mul_f32_e64 v0, v3, -v2
	s_nop 0
	v_add_u32_e32 v4, 0xa0, v172
	v_ashrrev_i32_e32 v5, 31, v4
	v_lshlrev_b64 v[8:9], 12, v[4:5]
	v_pk_fma_f32 v[4:5], v[80:81], v[2:3], v[0:1] op_sel:[0,1,0] op_sel_hi:[1,1,0]
	v_pk_fma_f32 v[6:7], v[82:83], v[2:3], v[0:1] op_sel:[0,1,0] op_sel_hi:[1,1,0]
	s_nop 0
	v_pk_fma_f32 v[6:7], v[138:139], v[6:7], v[142:143]
	v_pk_fma_f32 v[4:5], v[136:137], v[4:5], v[140:141]
	v_lshl_add_u64 v[8:9], v[8:9], 0, v[170:171]
	global_store_dwordx4 v8, v[4:7], s[30:31]
	s_nop 1
	v_pk_fma_f32 v[4:5], v[84:85], v[2:3], v[0:1] op_sel:[0,1,0] op_sel_hi:[1,1,0]
	v_pk_fma_f32 v[6:7], v[86:87], v[2:3], v[0:1] op_sel:[0,1,0] op_sel_hi:[1,1,0]
	v_pk_fma_f32 v[4:5], v[128:129], v[4:5], v[132:133]
	v_pk_fma_f32 v[6:7], v[130:131], v[6:7], v[134:135]
	global_store_dwordx4 v8, v[4:7], s[30:31] offset:64
	s_nop 1
	v_pk_fma_f32 v[4:5], v[88:89], v[2:3], v[0:1] op_sel:[0,1,0] op_sel_hi:[1,1,0]
	v_pk_fma_f32 v[6:7], v[90:91], v[2:3], v[0:1] op_sel:[0,1,0] op_sel_hi:[1,1,0]
	v_pk_fma_f32 v[4:5], v[120:121], v[4:5], v[124:125]
	v_pk_fma_f32 v[6:7], v[122:123], v[6:7], v[126:127]
	global_store_dwordx4 v8, v[4:7], s[30:31] offset:512
	s_nop 1
	v_pk_fma_f32 v[4:5], v[92:93], v[2:3], v[0:1] op_sel:[0,1,0] op_sel_hi:[1,1,0]
	v_pk_fma_f32 v[0:1], v[94:95], v[2:3], v[0:1] op_sel:[0,1,0] op_sel_hi:[1,1,0]
	s_nop 0
	v_pk_fma_f32 v[2:3], v[114:115], v[0:1], v[118:119]
	v_pk_fma_f32 v[0:1], v[112:113], v[4:5], v[116:117]
	global_store_dwordx4 v8, v[0:3], s[30:31] offset:576
	v_mul_f32_e64 v4, v151, -v150
	s_nop 0
	v_add_u32_e32 v0, 0xb0, v172
	v_ashrrev_i32_e32 v1, 31, v0
	v_lshlrev_b64 v[6:7], 12, v[0:1]
	v_pk_fma_f32 v[0:1], v[108:109], v[150:151], v[4:5] op_sel:[0,1,0] op_sel_hi:[1,1,0]
	v_pk_fma_f32 v[2:3], v[110:111], v[150:151], v[4:5] op_sel:[0,1,0] op_sel_hi:[1,1,0]
	s_nop 0
	v_pk_fma_f32 v[2:3], v[138:139], v[2:3], v[142:143]
	v_pk_fma_f32 v[0:1], v[136:137], v[0:1], v[140:141]
	v_lshl_add_u64 v[6:7], v[6:7], 0, v[170:171]
	global_store_dwordx4 v6, v[0:3], s[30:31]
	s_nop 1
	v_pk_fma_f32 v[0:1], v[104:105], v[150:151], v[4:5] op_sel:[0,1,0] op_sel_hi:[1,1,0]
	v_pk_fma_f32 v[2:3], v[106:107], v[150:151], v[4:5] op_sel:[0,1,0] op_sel_hi:[1,1,0]
	v_pk_fma_f32 v[0:1], v[128:129], v[0:1], v[132:133]
	v_pk_fma_f32 v[2:3], v[130:131], v[2:3], v[134:135]
	global_store_dwordx4 v6, v[0:3], s[30:31] offset:64
	s_nop 1
	v_pk_fma_f32 v[0:1], v[100:101], v[150:151], v[4:5] op_sel:[0,1,0] op_sel_hi:[1,1,0]
	v_pk_fma_f32 v[2:3], v[102:103], v[150:151], v[4:5] op_sel:[0,1,0] op_sel_hi:[1,1,0]
	v_pk_fma_f32 v[0:1], v[120:121], v[0:1], v[124:125]
	v_pk_fma_f32 v[2:3], v[122:123], v[2:3], v[126:127]
	global_store_dwordx4 v6, v[0:3], s[30:31] offset:512
	s_nop 1
	v_pk_fma_f32 v[0:1], v[96:97], v[150:151], v[4:5] op_sel:[0,1,0] op_sel_hi:[1,1,0]
	v_pk_fma_f32 v[2:3], v[98:99], v[150:151], v[4:5] op_sel:[0,1,0] op_sel_hi:[1,1,0]
	v_pk_fma_f32 v[0:1], v[112:113], v[0:1], v[116:117]
	v_pk_fma_f32 v[2:3], v[114:115], v[2:3], v[118:119]
	global_store_dwordx4 v6, v[0:3], s[30:31] offset:576
	s_cbranch_vccnz .LBB0_924
	s_mov_b32 s95, s92
	s_mov_b32 s94, s93
	s_mov_b32 s66, s91
	s_barrier
	s_branch .LBB0_924
